# mods_reduce partial loads issued together; attention queue pop atomic issued before the output-store drain, item index via ds ops
# speedup vs baseline: 1.0057x; 1.0057x over previous
.LBB0_34:
	s_mov_b32 s10, 0x38e38e39
	v_mul_hi_i32 v2, v4, s10
	v_lshrrev_b32_e32 v5, 31, v2
	v_ashrrev_i32_e32 v2, 12, v2
	v_add_u32_e32 v2, v2, v5
	v_mul_hi_i32 v5, v4, s11
	s_waitcnt vmcnt(0)
	v_lshrrev_b32_e32 v6, 31, v5
	v_ashrrev_i32_e32 v5, 10, v5
	v_add_u32_e32 v5, v5, v6
	v_mul_i32_i24_e32 v5, 0x1800, v5
	v_sub_u32_e32 v5, v4, v5
	s_movk_i32 s10, 0x1800
	v_mad_i32_i24 v6, v2, s10, v5
	v_ashrrev_i32_e32 v7, 31, v6
	v_lshl_add_u64 v[6:7], v[6:7], 2, s[18:19]
	v_ashrrev_i32_e32 v5, 31, v4
	global_load_dword v2, v[6:7], off
	v_lshlrev_b64 v[6:7], 2, v[4:5]
	v_lshl_add_u64 v[8:9], s[14:15], 0, v[6:7]
	global_load_dword v5, v[8:9], off
	v_add_co_u32_e32 v10, vcc, s16, v8
	s_nop 1
	v_addc_co_u32_e32 v11, vcc, 0, v9, vcc
	global_load_dword v12, v[10:11], off
	s_mov_b32 s10, 0x90000
	v_add_co_u32_e32 v10, vcc, s10, v8
	s_nop 1
	v_addc_co_u32_e32 v11, vcc, 0, v9, vcc
	global_load_dword v13, v[10:11], off
	s_mov_b32 s10, 0xd8000
	v_add_co_u32_e32 v10, vcc, s10, v8
	s_nop 1
	v_addc_co_u32_e32 v11, vcc, 0, v9, vcc
	global_load_dword v14, v[10:11], off
	s_mov_b32 s10, 0x120000
	v_add_co_u32_e32 v10, vcc, s10, v8
	s_nop 1
	v_addc_co_u32_e32 v11, vcc, 0, v9, vcc
	global_load_dword v15, v[10:11], off
	s_mov_b32 s10, 0x168000
	v_add_co_u32_e32 v10, vcc, s10, v8
	s_nop 1
	v_addc_co_u32_e32 v11, vcc, 0, v9, vcc
	global_load_dword v16, v[10:11], off
	s_mov_b32 s10, 0x1b0000
	v_add_co_u32_e32 v10, vcc, s10, v8
	s_nop 1
	v_addc_co_u32_e32 v11, vcc, 0, v9, vcc
	global_load_dword v17, v[10:11], off
	s_mov_b32 s10, 0x1f8000
	v_add_co_u32_e32 v10, vcc, s10, v8
	s_nop 1
	v_addc_co_u32_e32 v11, vcc, 0, v9, vcc
	global_load_dword v18, v[10:11], off
	v_add_u32_e32 v4, s0, v4
	v_lshl_add_u64 v[6:7], s[12:13], 0, v[6:7]
	s_mov_b32 s10, 0x11fff
	v_cmp_lt_i32_e32 vcc, s10, v4
	s_or_b64 s[8:9], vcc, s[8:9]
	s_waitcnt vmcnt(0)
	v_add_f32_e32 v2, v2, v5
	v_add_f32_e32 v2, v2, v12
	v_add_f32_e32 v2, v2, v13
	v_add_f32_e32 v2, v2, v14
	v_add_f32_e32 v2, v2, v15
	v_add_f32_e32 v2, v2, v16
	v_add_f32_e32 v2, v2, v17
	v_add_f32_e32 v2, v2, v18
	global_store_dword v[6:7], v2, off
	s_andn2_b64 exec, exec, s[8:9]
	s_cbranch_execnz .LBB0_34

.LBB0_312:
	s_mov_b64 s[2:3], exec
	v_readlane_b32 s4, v253, 50
	v_readlane_b32 s5, v253, 51
	v_readlane_b32 s6, v251, 49
	v_readlane_b32 s7, v251, 50
	s_and_b64 s[4:5], s[2:3], s[4:5]
	s_mov_b64 exec, s[4:5]
	s_cbranch_execz .Lpop_noissue
	v_mov_b32_e32 v255, 1
	s_nop 2
	global_atomic_add v255, v3, v255, s[6:7] sc0
.Lpop_noissue:
	s_mov_b64 exec, s[2:3]
	s_waitcnt vmcnt(0) lgkmcnt(0)
	s_barrier
	s_mov_b64 exec, s[4:5]
	s_cbranch_execz .LBB0_316
	ds_write_b32 v188, v255
.LBB0_316:
	s_or_b64 exec, exec, s[2:3]
	s_waitcnt lgkmcnt(0)
	s_barrier
	ds_read_b32 v2, v188
	s_mov_b64 s[2:3], -1
	s_waitcnt lgkmcnt(0)
	v_readfirstlane_b32 s39, v2
	s_cmpk_gt_i32 s39, 0x43f
	s_cbranch_scc1 .LBB0_311
	s_cmpk_lt_i32 s39, 0x80
	s_cselect_b64 s[2:3], -1, 0
	s_cmpk_gt_i32 s39, 0x7f
	s_mov_b64 s[4:5], -1
	s_cbranch_scc1 .LBB0_319
	s_ashr_i32 s0, s39, 6
	s_lshl_b32 s6, s0, 8
	s_lshl_b32 s4, s0, 12
	s_lshl_b32 s5, s39, 8
	s_add_i32 s8, s6, 0x4000
	s_addk_i32 s4, 0x2000
	s_and_b32 s36, s5, 0xf00
	s_ashr_i32 s9, s8, 31
	s_bfe_u32 s18, s39, 0x20004
	s_or_b32 s16, s4, s36
	s_lshl_b64 s[10:11], s[8:9], 9
	v_readlane_b32 s20, v253, 44
	v_readlane_b32 s21, v253, 45
	s_add_u32 s0, s20, s10
	s_addc_u32 s5, s21, s11
	s_lshl_b32 s19, s18, 7
	s_add_u32 s12, s0, s19
	s_addc_u32 s13, s5, 0
	s_lshl_b64 s[8:9], s[8:9], 6
	v_readlane_b32 s22, v253, 48
	v_readlane_b32 s23, v253, 49
	s_add_u32 s26, s22, s8
	s_addc_u32 s27, s23, s9
	s_mul_i32 s0, s18, 0x210000
	v_readlane_b32 s8, v253, 46
	v_readlane_b32 s9, v253, 47
	s_add_u32 s0, s8, s0
	s_addc_u32 s10, s9, 0
	s_ashr_i32 s7, s6, 31
	s_lshl_b64 s[6:7], s[6:7], 1
	s_add_u32 s5, s0, s6
	s_addc_u32 s6, s10, s7
	s_add_u32 s14, s5, 0x8000
	s_addc_u32 s15, s6, 0
	s_ashr_i32 s5, s4, 31
	s_lshl_b64 s[6:7], s[4:5], 9
	s_add_u32 s6, s20, s6
	s_addc_u32 s7, s21, s7
	s_add_u32 s6, s6, s19
	s_addc_u32 s7, s7, 0
	s_lshl_b64 s[8:9], s[4:5], 6
	s_add_u32 s24, s22, s8
	s_addc_u32 s25, s23, s9
	s_lshl_b64 s[4:5], s[4:5], 1
	s_add_u32 s8, s0, s4
	s_addc_u32 s9, s10, s5
	s_ashr_i32 s17, s16, 31
	s_mul_i32 s4, s16, 0x300
	v_readlane_b32 s10, v253, 42
	s_mul_hi_i32 s0, s16, 0x300
	v_readlane_b32 s11, v253, 43
	s_add_u32 s4, s10, s4
	s_addc_u32 s0, s11, s0
	s_mulk_i32 s18, 0xc0
	s_add_u32 s10, s4, s18
	s_addc_u32 s11, s0, 0
	s_lshl_b64 s[4:5], s[16:17], 11
	v_readlane_b32 s0, v251, 32
	s_add_u32 s0, s0, s4
	v_readlane_b32 s4, v251, 33
	s_addc_u32 s4, s4, s5
	s_add_u32 s0, s0, s19
	s_addc_u32 s4, s4, 0
	s_add_u32 s16, s0, 0x300
	s_addc_u32 s17, s4, 0
	v_writelane_b32 v251, s16, 52
	s_mov_b64 s[4:5], 0
	s_nop 0
	v_writelane_b32 v251, s17, 53
